# baseline (speedup 1.0000x reference)
; #define PG8_STAGE(bufoff, gbase, voff) do { _Pragma("unroll") for (int _i = 0; _i < 2; ++_i) \
;         __builtin_amdgcn_global_load_lds((const unsigned*)((const char*)(gbase) + (voff)[_i]), (PG8_LAS unsigned*)(lds + (bufoff) + ldsw + _i * 8192), 16, 0, 0); } while (0)
; #define PG8_LDA(dst, b, h) do { _Pragma("unroll") for (int m = 0; m < 4; ++m) _Pragma("unroll") for (int k = 0; k < 2; ++k) dst[m][k] = *(const PG8_LAS bf16x8*)(lds + PG8_SA(b, h) + aoff + m * 2048 + k * 1024); } while (0)
; #define PG8_LDB(dst, b, h) do { _Pragma("unroll") for (int n = 0; n < 2; ++n) _Pragma("unroll") for (int k = 0; k < 2; ++k) dst[n][k] = *(const PG8_LAS bf16x8*)(lds + PG8_SB(b, h) + boff + n * 2048 + k * 1024); } while (0)
; #define PG8_MMA(ai, bj, At, Bt) do { __builtin_amdgcn_s_setprio(1); _Pragma("unroll") for (int m = 0; m < 4; ++m) _Pragma("unroll") for (int n = 0; n < 2; ++n) _Pragma("unroll") for (int k = 0; k < 2; ++k) \
;         acc[ai][bj][m][n] = __builtin_amdgcn_mfma_f32_16x16x32_bf16(Bt[n][k], At[m][k], acc[ai][bj][m][n], 0, 0, 0); __builtin_amdgcn_s_setprio(0); } while (0)
; #define PG8_WAIT_V(n) asm volatile("s_waitcnt vmcnt(" #n ")" ::: "memory")
; #define PG8_WAIT_L(n) asm volatile("s_waitcnt lgkmcnt(" #n ")" ::: "memory")
; #define PG8_BAR __builtin_amdgcn_s_barrier()
; #define PG8_SCHED __builtin_amdgcn_sched_barrier(0)
; template <class Epi, class Sched, bool ALIGN_EPI = false, bool SP2 = false>
; __device__ __forceinline__ void gemm_phase(PG8_LAS unsigned char* lds, const Gemm g, const Sched& S, const Epi& E) {
;     ...
;             PG8_LDB(B0, 0, 0); PG8_LDB(B1, 0, 1); PG8_SCHED; PG8_LDA(At, 0, 0); PG8_STAGE(PG8_SA(1, 1), a1 + hstep, voffA);
;             PG8_WAIT_V(8); PG8_WAIT_L(0); PG8_BAR; PG8_MMA(0, 0, At, B0); PG8_MMA(0, 1, At, B1); PG8_BAR; PG8_SCHED;
;             PG8_LDA(At, 0, 1); PG8_STAGE(PG8_SB(0, 0), b2, voffB); PG8_STAGE(PG8_SB(0, 1), b2 + hstep, voffB); PG8_STAGE(PG8_SA(0, 0), a2, voffA);
;             PG8_WAIT_V(8); PG8_WAIT_L(0); PG8_BAR; PG8_MMA(1, 0, At, B0); PG8_MMA(1, 1, At, B1); PG8_BAR; PG8_SCHED;
.LBB0_337:
	s_add_u32 s42, s92, 0xfffc0080
	s_addc_u32 s43, s93, -1
	s_add_i32 s58, 0, 0x10000
	s_cmp_eq_u32 s71, 12
	s_cselect_b32 s55, s69, s43
	s_cselect_b32 s54, s85, s42
	v_add_u32_e32 v142, s58, v144
	s_cselect_b32 s43, s37, s70
	s_cselect_b32 s42, vcc_lo, vcc_hi
	s_add_i32 s9, 0, 0x14000
	ds_read_b128 v[148:151], v142
	ds_read_b128 v[152:155], v142 offset:1024
	ds_read_b128 v[156:159], v142 offset:2048
	ds_read_b128 v[160:163], v142 offset:3072
	v_add_u32_e32 v142, s9, v144
	ds_read_b128 v[164:167], v142
	ds_read_b128 v[168:171], v142 offset:1024
	ds_read_b128 v[172:175], v142 offset:2048
	ds_read_b128 v[176:179], v142 offset:3072
	v_lshl_add_u64 v[142:143], s[92:93], 0, v[140:141]
	s_add_i32 m0, s91, 0xc000
	ds_read_b128 v[180:183], v146
	ds_read_b128 v[184:187], v146 offset:1024
	ds_read_b128 v[188:191], v146 offset:2048
	ds_read_b128 v[192:195], v146 offset:3072
	ds_read_b128 v[196:199], v146 offset:4096
	ds_read_b128 v[200:203], v146 offset:5120
	ds_read_b128 v[204:207], v146 offset:6144
	ds_read_b128 v[214:217], v146 offset:7168
	global_load_lds_dwordx4 v[142:143], off
	v_lshl_add_u64 v[142:143], s[92:93], 0, v[138:139]
	s_add_i32 m0, s91, 0xe000
	s_nop 0
	global_load_lds_dwordx4 v[142:143], off
	s_waitcnt vmcnt(8)
	s_waitcnt lgkmcnt(0)
	s_barrier
	s_setprio 1
	s_waitcnt lgkmcnt(0)
	v_mfma_f32_16x16x32_bf16 v[128:131], v[148:151], v[180:183], v[128:131]
	v_mfma_f32_16x16x32_bf16 v[120:123], v[156:159], v[180:183], v[120:123]
	v_mfma_f32_16x16x32_bf16 v[112:115], v[148:151], v[188:191], v[112:115]
	v_mfma_f32_16x16x32_bf16 v[104:107], v[156:159], v[188:191], v[104:107]
	v_mfma_f32_16x16x32_bf16 v[96:99], v[148:151], v[196:199], v[96:99]
	v_mfma_f32_16x16x32_bf16 v[88:91], v[156:159], v[196:199], v[88:91]
	v_mfma_f32_16x16x32_bf16 v[80:83], v[148:151], v[204:207], v[80:83]
	v_mfma_f32_16x16x32_bf16 v[72:75], v[156:159], v[204:207], v[72:75]
	v_mfma_f32_16x16x32_bf16 v[128:131], v[152:155], v[184:187], v[128:131]
	v_mfma_f32_16x16x32_bf16 v[120:123], v[160:163], v[184:187], v[120:123]
	v_mfma_f32_16x16x32_bf16 v[112:115], v[152:155], v[192:195], v[112:115]
	v_mfma_f32_16x16x32_bf16 v[104:107], v[160:163], v[192:195], v[104:107]
	v_mfma_f32_16x16x32_bf16 v[96:99], v[152:155], v[200:203], v[96:99]
	v_mfma_f32_16x16x32_bf16 v[88:91], v[160:163], v[200:203], v[88:91]
	v_mfma_f32_16x16x32_bf16 v[80:83], v[152:155], v[214:217], v[80:83]
	v_mfma_f32_16x16x32_bf16 v[72:75], v[160:163], v[214:217], v[72:75]
	s_setprio 0
	s_setprio 1
	v_mfma_f32_16x16x32_bf16 v[124:127], v[164:167], v[180:183], v[124:127]
	v_mfma_f32_16x16x32_bf16 v[116:119], v[172:175], v[180:183], v[116:119]
	v_mfma_f32_16x16x32_bf16 v[108:111], v[164:167], v[188:191], v[108:111]
	v_mfma_f32_16x16x32_bf16 v[100:103], v[172:175], v[188:191], v[100:103]
	v_mfma_f32_16x16x32_bf16 v[92:95], v[164:167], v[196:199], v[92:95]
	v_mfma_f32_16x16x32_bf16 v[84:87], v[172:175], v[196:199], v[84:87]
	v_mfma_f32_16x16x32_bf16 v[76:79], v[164:167], v[204:207], v[76:79]
	v_mfma_f32_16x16x32_bf16 v[68:71], v[172:175], v[204:207], v[68:71]
	v_mfma_f32_16x16x32_bf16 v[124:127], v[168:171], v[184:187], v[124:127]
	v_mfma_f32_16x16x32_bf16 v[116:119], v[176:179], v[184:187], v[116:119]
	v_mfma_f32_16x16x32_bf16 v[108:111], v[168:171], v[192:195], v[108:111]
	v_mfma_f32_16x16x32_bf16 v[100:103], v[176:179], v[192:195], v[100:103]
	v_mfma_f32_16x16x32_bf16 v[92:95], v[168:171], v[200:203], v[92:95]
	v_mfma_f32_16x16x32_bf16 v[84:87], v[176:179], v[200:203], v[84:87]
	v_mfma_f32_16x16x32_bf16 v[76:79], v[168:171], v[214:217], v[76:79]
	v_mfma_f32_16x16x32_bf16 v[68:71], v[176:179], v[214:217], v[68:71]
	s_setprio 0
	s_barrier
	s_add_i32 s58, s58, s38
	v_lshl_add_u64 v[142:143], s[42:43], 0, v[134:135]
	s_mov_b32 m0, s58
	ds_read_b128 v[180:183], v146 offset:16384
	ds_read_b128 v[184:187], v146 offset:17408
	ds_read_b128 v[188:191], v146 offset:18432
	ds_read_b128 v[192:195], v146 offset:19456
	ds_read_b128 v[196:199], v146 offset:20480
	ds_read_b128 v[200:203], v146 offset:21504
	ds_read_b128 v[204:207], v146 offset:22528
	ds_read_b128 v[214:217], v146 offset:23552
	global_load_lds_dwordx4 v[142:143], off
	s_add_i32 m0, s58, 0x2000
	s_add_u32 s58, s42, 0x40000
	v_lshl_add_u64 v[218:219], s[42:43], 0, v[0:1]
	s_addc_u32 s59, s43, 0
	s_add_i32 s9, s9, s38
	global_load_lds_dwordx4 v[218:219], off
	v_lshl_add_u64 v[220:221], s[58:59], 0, v[134:135]
	s_mov_b32 m0, s9
	v_lshl_add_u64 v[222:223], s[54:55], 0, v[132:133]
	global_load_lds_dwordx4 v[220:221], off
	v_lshl_add_u64 v[220:221], s[58:59], 0, v[0:1]
	s_add_i32 m0, s9, 0x2000
	s_nop 0
	global_load_lds_dwordx4 v[220:221], off
	v_lshl_add_u64 v[220:221], s[54:55], 0, v[136:137]
	s_mov_b32 m0, s91
	s_nop 0
	global_load_lds_dwordx4 v[220:221], off
	s_mov_b32 m0, s45
	s_nop 0
	global_load_lds_dwordx4 v[222:223], off
	s_waitcnt vmcnt(8)
	s_waitcnt lgkmcnt(0)
	s_barrier
; #define PG8_STAGE(bufoff, gbase, voff) do { _Pragma("unroll") for (int _i = 0; _i < 2; ++_i) \
;         __builtin_amdgcn_global_load_lds((const unsigned*)((const char*)(gbase) + (voff)[_i]), (PG8_LAS unsigned*)(lds + (bufoff) + ldsw + _i * 8192), 16, 0, 0); } while (0)
; #define PG8_LDA(dst, b, h) do { _Pragma("unroll") for (int m = 0; m < 4; ++m) _Pragma("unroll") for (int k = 0; k < 2; ++k) dst[m][k] = *(const PG8_LAS bf16x8*)(lds + PG8_SA(b, h) + aoff + m * 2048 + k * 1024); } while (0)
; #define PG8_LDB(dst, b, h) do { _Pragma("unroll") for (int n = 0; n < 2; ++n) _Pragma("unroll") for (int k = 0; k < 2; ++k) dst[n][k] = *(const PG8_LAS bf16x8*)(lds + PG8_SB(b, h) + boff + n * 2048 + k * 1024); } while (0)
; #define PG8_MMA(ai, bj, At, Bt) do { __builtin_amdgcn_s_setprio(1); _Pragma("unroll") for (int m = 0; m < 4; ++m) _Pragma("unroll") for (int n = 0; n < 2; ++n) _Pragma("unroll") for (int k = 0; k < 2; ++k) \
;         acc[ai][bj][m][n] = __builtin_amdgcn_mfma_f32_16x16x32_bf16(Bt[n][k], At[m][k], acc[ai][bj][m][n], 0, 0, 0); __builtin_amdgcn_s_setprio(0); } while (0)
; #define PG8_WAIT_V(n) asm volatile("s_waitcnt vmcnt(" #n ")" ::: "memory")
; #define PG8_WAIT_L(n) asm volatile("s_waitcnt lgkmcnt(" #n ")" ::: "memory")
; #define PG8_BAR __builtin_amdgcn_s_barrier()
; #define PG8_SCHED __builtin_amdgcn_sched_barrier(0)
; template <class Epi, class Sched, bool ALIGN_EPI = false, bool SP2 = false>
; __device__ __forceinline__ void gemm_phase(PG8_LAS unsigned char* lds, const Gemm g, const Sched& S, const Epi& E) {
;     ...
;             PG8_WAIT_V(8); PG8_WAIT_L(0); PG8_BAR; PG8_MMA(1, 0, At, B0); PG8_MMA(1, 1, At, B1); PG8_BAR; PG8_SCHED;
;             PG8_LDB(B0, 1, 0); PG8_LDB(B1, 1, 1); PG8_SCHED; PG8_LDA(At, 1, 0); PG8_STAGE(PG8_SA(0, 1), a2 + hstep, voffA);
;             PG8_WAIT_V(8); PG8_WAIT_L(0); PG8_BAR; PG8_MMA(0, 0, At, B0); PG8_MMA(0, 1, At, B1); PG8_BAR; PG8_SCHED;
	s_setprio 1
	s_waitcnt lgkmcnt(0)
	v_mfma_f32_16x16x32_bf16 v[64:67], v[148:151], v[180:183], v[64:67]
	v_mfma_f32_16x16x32_bf16 v[56:59], v[156:159], v[180:183], v[56:59]
	v_mfma_f32_16x16x32_bf16 v[48:51], v[148:151], v[188:191], v[48:51]
	v_mfma_f32_16x16x32_bf16 v[40:43], v[156:159], v[188:191], v[40:43]
	v_mfma_f32_16x16x32_bf16 v[32:35], v[148:151], v[196:199], v[32:35]
	v_mfma_f32_16x16x32_bf16 v[24:27], v[156:159], v[196:199], v[24:27]
	v_mfma_f32_16x16x32_bf16 v[16:19], v[148:151], v[204:207], v[16:19]
	v_mfma_f32_16x16x32_bf16 v[8:11], v[156:159], v[204:207], v[8:11]
	v_mfma_f32_16x16x32_bf16 v[64:67], v[152:155], v[184:187], v[64:67]
	v_mfma_f32_16x16x32_bf16 v[56:59], v[160:163], v[184:187], v[56:59]
	v_mfma_f32_16x16x32_bf16 v[48:51], v[152:155], v[192:195], v[48:51]
	v_mfma_f32_16x16x32_bf16 v[40:43], v[160:163], v[192:195], v[40:43]
	v_mfma_f32_16x16x32_bf16 v[32:35], v[152:155], v[200:203], v[32:35]
	v_mfma_f32_16x16x32_bf16 v[24:27], v[160:163], v[200:203], v[24:27]
	v_mfma_f32_16x16x32_bf16 v[16:19], v[152:155], v[214:217], v[16:19]
	v_mfma_f32_16x16x32_bf16 v[8:11], v[160:163], v[214:217], v[8:11]
	s_setprio 0
	s_setprio 1
	v_mfma_f32_16x16x32_bf16 v[60:63], v[164:167], v[180:183], v[60:63]
	v_mfma_f32_16x16x32_bf16 v[52:55], v[172:175], v[180:183], v[52:55]
	v_mfma_f32_16x16x32_bf16 v[44:47], v[164:167], v[188:191], v[44:47]
	v_mfma_f32_16x16x32_bf16 v[36:39], v[172:175], v[188:191], v[36:39]
	v_mfma_f32_16x16x32_bf16 v[28:31], v[164:167], v[196:199], v[28:31]
	v_mfma_f32_16x16x32_bf16 v[20:23], v[172:175], v[196:199], v[20:23]
	v_mfma_f32_16x16x32_bf16 v[12:15], v[164:167], v[204:207], v[12:15]
	v_mfma_f32_16x16x32_bf16 v[4:7], v[172:175], v[204:207], v[4:7]
	v_mfma_f32_16x16x32_bf16 v[60:63], v[168:171], v[184:187], v[60:63]
	v_mfma_f32_16x16x32_bf16 v[52:55], v[176:179], v[184:187], v[52:55]
	v_mfma_f32_16x16x32_bf16 v[44:47], v[168:171], v[192:195], v[44:47]
	v_mfma_f32_16x16x32_bf16 v[36:39], v[176:179], v[192:195], v[36:39]
	v_mfma_f32_16x16x32_bf16 v[28:31], v[168:171], v[200:203], v[28:31]
	v_mfma_f32_16x16x32_bf16 v[20:23], v[176:179], v[200:203], v[20:23]
	v_mfma_f32_16x16x32_bf16 v[12:15], v[168:171], v[214:217], v[12:15]
	v_mfma_f32_16x16x32_bf16 v[4:7], v[176:179], v[214:217], v[4:7]
	s_setprio 0
	s_barrier
	s_add_i32 s9, 0, 0x18000
	v_add_u32_e32 v147, s9, v144
	s_add_i32 s58, 0, 0x1c000
	ds_read_b128 v[148:151], v147
	ds_read_b128 v[152:155], v147 offset:1024
	ds_read_b128 v[156:159], v147 offset:2048
	ds_read_b128 v[160:163], v147 offset:3072
	v_add_u32_e32 v147, s58, v144
	ds_read_b128 v[164:167], v147
	ds_read_b128 v[168:171], v147 offset:1024
	ds_read_b128 v[172:175], v147 offset:2048
	ds_read_b128 v[176:179], v147 offset:3072
	s_add_u32 s54, s54, 0x40000
	s_addc_u32 s55, s55, 0
	s_mov_b32 m0, s62
	v_lshl_add_u64 v[224:225], s[54:55], 0, v[136:137]
	ds_read_b128 v[180:183], v146 offset:32768
	ds_read_b128 v[184:187], v146 offset:33792
	ds_read_b128 v[188:191], v146 offset:34816
	ds_read_b128 v[192:195], v146 offset:35840
	ds_read_b128 v[196:199], v146 offset:36864
	ds_read_b128 v[200:203], v146 offset:37888
	ds_read_b128 v[204:207], v146 offset:38912
	ds_read_b128 v[214:217], v146 offset:39936
	global_load_lds_dwordx4 v[224:225], off
	v_lshl_add_u64 v[224:225], s[54:55], 0, v[132:133]
	s_mov_b32 m0, s63
	s_nop 0
	global_load_lds_dwordx4 v[224:225], off
	s_waitcnt vmcnt(8)
	s_waitcnt lgkmcnt(0)
	s_barrier
	s_setprio 1
	s_waitcnt lgkmcnt(0)
	v_mfma_f32_16x16x32_bf16 v[128:131], v[148:151], v[180:183], v[128:131]
	v_mfma_f32_16x16x32_bf16 v[120:123], v[156:159], v[180:183], v[120:123]
	v_mfma_f32_16x16x32_bf16 v[112:115], v[148:151], v[188:191], v[112:115]
	v_mfma_f32_16x16x32_bf16 v[104:107], v[156:159], v[188:191], v[104:107]
	v_mfma_f32_16x16x32_bf16 v[96:99], v[148:151], v[196:199], v[96:99]
	v_mfma_f32_16x16x32_bf16 v[88:91], v[156:159], v[196:199], v[88:91]
	v_mfma_f32_16x16x32_bf16 v[80:83], v[148:151], v[204:207], v[80:83]
	v_mfma_f32_16x16x32_bf16 v[72:75], v[156:159], v[204:207], v[72:75]
	v_mfma_f32_16x16x32_bf16 v[128:131], v[152:155], v[184:187], v[128:131]
	v_mfma_f32_16x16x32_bf16 v[120:123], v[160:163], v[184:187], v[120:123]
	v_mfma_f32_16x16x32_bf16 v[112:115], v[152:155], v[192:195], v[112:115]
	v_mfma_f32_16x16x32_bf16 v[104:107], v[160:163], v[192:195], v[104:107]
	v_mfma_f32_16x16x32_bf16 v[96:99], v[152:155], v[200:203], v[96:99]
	v_mfma_f32_16x16x32_bf16 v[88:91], v[160:163], v[200:203], v[88:91]
	v_mfma_f32_16x16x32_bf16 v[80:83], v[152:155], v[214:217], v[80:83]
	v_mfma_f32_16x16x32_bf16 v[72:75], v[160:163], v[214:217], v[72:75]
	s_setprio 0
	s_setprio 1
	v_mfma_f32_16x16x32_bf16 v[124:127], v[164:167], v[180:183], v[124:127]
	v_mfma_f32_16x16x32_bf16 v[116:119], v[172:175], v[180:183], v[116:119]
	v_mfma_f32_16x16x32_bf16 v[108:111], v[164:167], v[188:191], v[108:111]
	v_mfma_f32_16x16x32_bf16 v[100:103], v[172:175], v[188:191], v[100:103]
	v_mfma_f32_16x16x32_bf16 v[92:95], v[164:167], v[196:199], v[92:95]
	v_mfma_f32_16x16x32_bf16 v[84:87], v[172:175], v[196:199], v[84:87]
	v_mfma_f32_16x16x32_bf16 v[76:79], v[164:167], v[204:207], v[76:79]
	v_mfma_f32_16x16x32_bf16 v[68:71], v[172:175], v[204:207], v[68:71]
	v_mfma_f32_16x16x32_bf16 v[124:127], v[168:171], v[184:187], v[124:127]
	v_mfma_f32_16x16x32_bf16 v[116:119], v[176:179], v[184:187], v[116:119]
	v_mfma_f32_16x16x32_bf16 v[108:111], v[168:171], v[192:195], v[108:111]
	v_mfma_f32_16x16x32_bf16 v[100:103], v[176:179], v[192:195], v[100:103]
	v_mfma_f32_16x16x32_bf16 v[92:95], v[168:171], v[200:203], v[92:95]
	v_mfma_f32_16x16x32_bf16 v[84:87], v[176:179], v[200:203], v[84:87]
	v_mfma_f32_16x16x32_bf16 v[76:79], v[168:171], v[214:217], v[76:79]
	v_mfma_f32_16x16x32_bf16 v[68:71], v[176:179], v[214:217], v[68:71]
	s_setprio 0
	s_barrier
;     __device__ __forceinline__ void operator()(const f32x4 (&acc)[2][2][4][2], const Unit& u, int wr, int wc, int fr, int fq) const {
;         int row0 = u.pm * BM + wr * 64 + fr; asm volatile("" : "+v"(row0)); const int col0 = u.pn * 128 + wc * 32 + 8 * fq;
; #pragma unroll
;         for (int ai = 0; ai < 2; ++ai)
; #pragma unroll
;             for (int m = 0; m < 4; ++m) { bf16_t* rowp = T + (size_t)(row0 + ai * HALF + m * 16) * ldc + col0; float t[8];
; #pragma unroll
;                 for (int n = 0; n < 2; ++n) { const f32x4 a = acc[ai][0][m][n], b = acc[ai][1][m][n];
; template <class Epi, class Sched, bool ALIGN_EPI = false, bool SP2 = false>
; __device__ __forceinline__ void gemm_phase(PG8_LAS unsigned char* lds, const Gemm g, const Sched& S, const Epi& E) {
;     ...
;             PG8_LDA(At, 1, 1); PG8_STAGE(PG8_SB(1, 0), b3, voffB); PG8_STAGE(PG8_SB(1, 1), b3 + hstep, voffB); PG8_STAGE(PG8_SA(1, 0), a3, voffA);
;             PG8_WAIT_V(8); PG8_WAIT_L(0); PG8_BAR; PG8_MMA(1, 0, At, B0); PG8_MMA(1, 1, At, B1); PG8_BAR; PG8_SCHED;
;             } else {
;             PG8_LDB(B0, 0, 0); PG8_SCHED; PG8_LDA(At, 0, 0); PG8_STAGE(PG8_SA(1, 1), a1 + hstep, voffA);
;             PG8_WAIT_L(8); PG8_BAR; PG8_WAIT_L(0); PG8_MMA(0, 0, At, B0); PG8_BAR; PG8_SCHED;
;             PG8_LDB(B1, 0, 1); PG8_STAGE(PG8_SB(0, 0), b2, voffB);
;             PG8_BAR; PG8_WAIT_L(0); PG8_MMA(0, 1, At, B1); PG8_BAR;
;             PG8_LDA(At, 0, 1); PG8_STAGE(PG8_SA(0, 0), a2, voffA);
;             PG8_BAR; PG8_WAIT_L(0); PG8_MMA(1, 0, At, B0); PG8_BAR; PG8_SCHED;
;             PG8_STAGE(PG8_SB(0, 1), b2 + hstep, voffB);
;             PG8_WAIT_V(6); PG8_BAR; PG8_MMA(1, 1, At, B1); PG8_BAR;
;             PG8_LDB(B0, 1, 0); PG8_SCHED; PG8_LDA(At, 1, 0); PG8_STAGE(PG8_SA(0, 1), a2 + hstep, voffA);
;             PG8_WAIT_L(8); PG8_BAR; PG8_WAIT_L(0); PG8_MMA(0, 0, At, B0); PG8_BAR; PG8_SCHED;
;             PG8_LDB(B1, 1, 1); PG8_STAGE(PG8_SB(1, 0), b3, voffB);
;             PG8_BAR; PG8_WAIT_L(0); PG8_MMA(0, 1, At, B1); PG8_BAR;
;             PG8_LDA(At, 1, 1); PG8_STAGE(PG8_SA(1, 0), a3, voffA);
;             PG8_BAR; PG8_WAIT_L(0); PG8_MMA(1, 0, At, B0); PG8_BAR; PG8_SCHED;
;             PG8_STAGE(PG8_SB(1, 1), b3 + hstep, voffB);
;             PG8_WAIT_V(6); PG8_BAR; PG8_MMA(1, 1, At, B1); PG8_BAR;
;             }
;         }
;         if constexpr (ALIGN_EPI) { if (wr == 0) PG8_BAR; }
	s_add_i32 s9, s9, s38
	v_lshl_add_u64 v[142:143], v[142:143], 0, s[52:53]
	s_mov_b32 m0, s9
	ds_read_b128 v[180:183], v146 offset:49152
	ds_read_b128 v[184:187], v146 offset:50176
	ds_read_b128 v[188:191], v146 offset:51200
	ds_read_b128 v[192:195], v146 offset:52224
	ds_read_b128 v[196:199], v146 offset:53248
	ds_read_b128 v[200:203], v146 offset:54272
	ds_read_b128 v[204:207], v146 offset:55296
	ds_read_b128 v[214:217], v146 offset:56320
	global_load_lds_dwordx4 v[142:143], off
	s_add_i32 m0, s9, 0x2000
	s_add_u32 s42, s42, 0x40080
	v_lshl_add_u64 v[142:143], v[218:219], 0, s[52:53]
	s_addc_u32 s43, s43, 0
	s_add_i32 s9, s58, s38
	global_load_lds_dwordx4 v[142:143], off
	v_lshl_add_u64 v[142:143], s[42:43], 0, v[134:135]
	s_mov_b32 m0, s9
	s_nop 0
	global_load_lds_dwordx4 v[142:143], off
	v_lshl_add_u64 v[142:143], s[42:43], 0, v[0:1]
	s_add_i32 m0, s9, 0x2000
	s_nop 0
	global_load_lds_dwordx4 v[142:143], off
	v_lshl_add_u64 v[142:143], v[220:221], 0, s[52:53]
	s_mov_b32 m0, s64
	s_nop 0
	global_load_lds_dwordx4 v[142:143], off
	v_lshl_add_u64 v[142:143], v[222:223], 0, s[52:53]
	s_mov_b32 m0, s65
	s_nop 0
	global_load_lds_dwordx4 v[142:143], off
	s_waitcnt vmcnt(8)
	s_waitcnt lgkmcnt(0)
	s_barrier
	s_setprio 1
	s_waitcnt lgkmcnt(0)
	v_mfma_f32_16x16x32_bf16 v[64:67], v[148:151], v[180:183], v[64:67]
	v_mfma_f32_16x16x32_bf16 v[56:59], v[156:159], v[180:183], v[56:59]
	v_mfma_f32_16x16x32_bf16 v[48:51], v[148:151], v[188:191], v[48:51]
	v_mfma_f32_16x16x32_bf16 v[40:43], v[156:159], v[188:191], v[40:43]
	v_mfma_f32_16x16x32_bf16 v[32:35], v[148:151], v[196:199], v[32:35]
	v_mfma_f32_16x16x32_bf16 v[24:27], v[156:159], v[196:199], v[24:27]
	v_mfma_f32_16x16x32_bf16 v[16:19], v[148:151], v[204:207], v[16:19]
	v_mfma_f32_16x16x32_bf16 v[8:11], v[156:159], v[204:207], v[8:11]
	v_mfma_f32_16x16x32_bf16 v[64:67], v[152:155], v[184:187], v[64:67]
	v_mfma_f32_16x16x32_bf16 v[56:59], v[160:163], v[184:187], v[56:59]
	v_mfma_f32_16x16x32_bf16 v[48:51], v[152:155], v[192:195], v[48:51]
	v_mfma_f32_16x16x32_bf16 v[40:43], v[160:163], v[192:195], v[40:43]
	v_mfma_f32_16x16x32_bf16 v[32:35], v[152:155], v[200:203], v[32:35]
	v_mfma_f32_16x16x32_bf16 v[24:27], v[160:163], v[200:203], v[24:27]
	v_mfma_f32_16x16x32_bf16 v[16:19], v[152:155], v[214:217], v[16:19]
	v_mfma_f32_16x16x32_bf16 v[8:11], v[160:163], v[214:217], v[8:11]
	s_setprio 0
	s_setprio 1
	v_mfma_f32_16x16x32_bf16 v[60:63], v[164:167], v[180:183], v[60:63]
	v_mfma_f32_16x16x32_bf16 v[52:55], v[172:175], v[180:183], v[52:55]
	v_mfma_f32_16x16x32_bf16 v[44:47], v[164:167], v[188:191], v[44:47]
	v_mfma_f32_16x16x32_bf16 v[36:39], v[172:175], v[188:191], v[36:39]
	v_mfma_f32_16x16x32_bf16 v[28:31], v[164:167], v[196:199], v[28:31]
	v_mfma_f32_16x16x32_bf16 v[20:23], v[172:175], v[196:199], v[20:23]
	v_mfma_f32_16x16x32_bf16 v[12:15], v[164:167], v[204:207], v[12:15]
	v_mfma_f32_16x16x32_bf16 v[4:7], v[172:175], v[204:207], v[4:7]
	v_mfma_f32_16x16x32_bf16 v[60:63], v[168:171], v[184:187], v[60:63]
	v_mfma_f32_16x16x32_bf16 v[52:55], v[176:179], v[184:187], v[52:55]
	v_mfma_f32_16x16x32_bf16 v[44:47], v[168:171], v[192:195], v[44:47]
	v_mfma_f32_16x16x32_bf16 v[36:39], v[176:179], v[192:195], v[36:39]
	v_mfma_f32_16x16x32_bf16 v[28:31], v[168:171], v[200:203], v[28:31]
	v_mfma_f32_16x16x32_bf16 v[20:23], v[176:179], v[200:203], v[20:23]
	v_mfma_f32_16x16x32_bf16 v[12:15], v[168:171], v[214:217], v[12:15]
	v_mfma_f32_16x16x32_bf16 v[4:7], v[176:179], v[214:217], v[4:7]
	s_setprio 0
	s_barrier
	s_add_i32 s71, s71, 2
	s_add_u32 vcc_hi, vcc_hi, 0x100
	s_addc_u32 s70, s70, 0
	s_add_u32 s92, s92, 0x100
	s_addc_u32 s93, s93, 0
	s_cmp_gt_u32 s71, 13
	s_cbranch_scc0 .LBB0_337
	s_and_b64 vcc, exec, s[34:35]
	s_cbranch_vccz .LBB0_340
	s_nop 0
.LBB0_340:
	v_mov_b32_e32 v164, 0xbfb8aa3b
	v_mov_b32_e32 v165, 0xbfb8aa3b
	v_lshl_or_b32 v148, s68, 7, v145
	v_lshl_add_u32 v147, s90, 8, v3
	v_ashrrev_i32_e32 v149, 31, v148
	v_mov_b64_e32 v[142:143], s[16:17]
	s_andn2_b64 vcc, exec, s[4:5]
	v_mad_i64_i32 v[150:151], s[42:43], v147, s40, v[142:143]
	s_nop 0
	v_pk_mul_f32 v[156:157], v[128:129], v[164:165]
	v_pk_mul_f32 v[158:159], v[130:131], v[164:165]
	v_pk_mul_f32 v[160:161], v[120:121], v[164:165]
	v_pk_mul_f32 v[162:163], v[122:123], v[164:165]
	v_exp_f32_e32 v156, v156
	v_exp_f32_e32 v157, v157
	v_exp_f32_e32 v158, v158
	v_exp_f32_e32 v159, v159
	v_exp_f32_e32 v160, v160
	v_exp_f32_e32 v161, v161
	v_exp_f32_e32 v162, v162
	v_exp_f32_e32 v163, v163
	v_pk_add_f32 v[156:157], v[156:157], 1.0 op_sel_hi:[1,0]
	v_pk_add_f32 v[158:159], v[158:159], 1.0 op_sel_hi:[1,0]
	v_pk_add_f32 v[160:161], v[160:161], 1.0 op_sel_hi:[1,0]
	v_pk_add_f32 v[162:163], v[162:163], 1.0 op_sel_hi:[1,0]
	v_rcp_f32_e32 v156, v156
	v_rcp_f32_e32 v157, v157
	v_rcp_f32_e32 v158, v158
	v_rcp_f32_e32 v159, v159
	v_rcp_f32_e32 v160, v160
	v_rcp_f32_e32 v161, v161
	v_rcp_f32_e32 v162, v162
	v_rcp_f32_e32 v163, v163
	v_pk_mul_f32 v[156:157], v[128:129], v[156:157]
	v_pk_mul_f32 v[158:159], v[130:131], v[158:159]
	v_pk_mul_f32 v[160:161], v[120:121], v[160:161]
	v_pk_mul_f32 v[162:163], v[122:123], v[162:163]
	v_pk_mul_f32 v[124:125], v[156:157], v[124:125]
	v_pk_mul_f32 v[126:127], v[158:159], v[126:127]
	v_pk_mul_f32 v[120:121], v[160:161], v[116:117]
	v_pk_mul_f32 v[128:129], v[162:163], v[118:119]
	v_cvt_pk_bf16_f32 v118, v124, v125
	v_lshlrev_b64 v[116:117], 1, v[148:149]
	v_lshl_add_u64 v[122:123], v[150:151], 0, v[116:117]
	v_cvt_pk_bf16_f32 v119, v126, v127
	v_cvt_pk_bf16_f32 v120, v120, v121
	v_cvt_pk_bf16_f32 v121, v128, v129
	global_store_dwordx4 v[122:123], v[118:121], off
	s_nop 1
	v_add_u32_e32 v118, 16, v147
; __device__ __forceinline__ unsigned cvt_pk_bf16(float lo, float hi) { unsigned r; asm volatile("v_cvt_pk_bf16_f32 %0, %1, %2" : "=v"(r) : "v"(lo), "v"(hi)); return r; }
;     __device__ __forceinline__ void operator()(const f32x4 (&acc)[2][2][4][2], const Unit& u, int wr, int wc, int fr, int fq) const {
;         int row0 = u.pm * BM + wr * 64 + fr; asm volatile("" : "+v"(row0)); const int col0 = u.pn * 128 + wc * 32 + 8 * fq;
; #pragma unroll
;         for (int ai = 0; ai < 2; ++ai)
; #pragma unroll
;             for (int m = 0; m < 4; ++m) { bf16_t* rowp = T + (size_t)(row0 + ai * HALF + m * 16) * ldc + col0; float t[8];
; #pragma unroll
;                 for (int n = 0; n < 2; ++n) { const f32x4 a = acc[ai][0][m][n], b = acc[ai][1][m][n];
; #pragma unroll
;                     for (int e = 0; e < 4; ++e) t[4 * n + e] = a[e] * __builtin_amdgcn_rcpf(1.0f + __expf(-a[e])) * b[e]; }
;                 u32x4 w; w.x = cvt_pk_bf16(t[0], t[1]); w.y = cvt_pk_bf16(t[2], t[3]); w.z = cvt_pk_bf16(t[4], t[5]); w.w = cvt_pk_bf16(t[6], t[7]);
;                 *(u32x4*)rowp = w; }
	v_mad_i64_i32 v[118:119], s[42:43], v118, s40, v[142:143]
	v_pk_mul_f32 v[156:157], v[112:113], v[164:165]
	v_pk_mul_f32 v[158:159], v[114:115], v[164:165]
	v_pk_mul_f32 v[160:161], v[104:105], v[164:165]
	v_pk_mul_f32 v[162:163], v[106:107], v[164:165]
	v_exp_f32_e32 v156, v156
	v_exp_f32_e32 v157, v157
	v_exp_f32_e32 v158, v158
	v_exp_f32_e32 v159, v159
	v_exp_f32_e32 v160, v160
	v_exp_f32_e32 v161, v161
	v_exp_f32_e32 v162, v162
	v_exp_f32_e32 v163, v163
	v_pk_add_f32 v[156:157], v[156:157], 1.0 op_sel_hi:[1,0]
	v_pk_add_f32 v[158:159], v[158:159], 1.0 op_sel_hi:[1,0]
	v_pk_add_f32 v[160:161], v[160:161], 1.0 op_sel_hi:[1,0]
	v_pk_add_f32 v[162:163], v[162:163], 1.0 op_sel_hi:[1,0]
	v_rcp_f32_e32 v156, v156
	v_rcp_f32_e32 v157, v157
	v_rcp_f32_e32 v158, v158
	v_rcp_f32_e32 v159, v159
	v_rcp_f32_e32 v160, v160
	v_rcp_f32_e32 v161, v161
	v_rcp_f32_e32 v162, v162
	v_rcp_f32_e32 v163, v163
	v_pk_mul_f32 v[156:157], v[112:113], v[156:157]
	v_pk_mul_f32 v[158:159], v[114:115], v[158:159]
	v_pk_mul_f32 v[160:161], v[104:105], v[160:161]
	v_pk_mul_f32 v[162:163], v[106:107], v[162:163]
	v_pk_mul_f32 v[108:109], v[156:157], v[108:109]
	v_pk_mul_f32 v[110:111], v[158:159], v[110:111]
	v_pk_mul_f32 v[112:113], v[160:161], v[100:101]
	v_mul_f32_e32 v106, v162, v102
	v_mul_f32_e32 v103, v163, v103
	v_lshl_add_u64 v[104:105], v[118:119], 0, v[116:117]
	v_cvt_pk_bf16_f32 v100, v108, v109
	v_cvt_pk_bf16_f32 v101, v110, v111
	v_cvt_pk_bf16_f32 v102, v112, v113
	v_cvt_pk_bf16_f32 v103, v106, v103
	global_store_dwordx4 v[104:105], v[100:103], off
	s_nop 1
	v_add_u32_e32 v100, 32, v147
	v_mad_i64_i32 v[100:101], s[42:43], v100, s40, v[142:143]
	v_pk_mul_f32 v[156:157], v[96:97], v[164:165]
	v_pk_mul_f32 v[158:159], v[98:99], v[164:165]
	v_pk_mul_f32 v[160:161], v[88:89], v[164:165]
	v_pk_mul_f32 v[162:163], v[90:91], v[164:165]
	v_exp_f32_e32 v156, v156
	v_exp_f32_e32 v157, v157
	v_exp_f32_e32 v158, v158
	v_exp_f32_e32 v159, v159
	v_exp_f32_e32 v160, v160
	v_exp_f32_e32 v161, v161
	v_exp_f32_e32 v162, v162
	v_exp_f32_e32 v163, v163
	v_pk_add_f32 v[156:157], v[156:157], 1.0 op_sel_hi:[1,0]
	v_pk_add_f32 v[158:159], v[158:159], 1.0 op_sel_hi:[1,0]
	v_pk_add_f32 v[160:161], v[160:161], 1.0 op_sel_hi:[1,0]
	v_pk_add_f32 v[162:163], v[162:163], 1.0 op_sel_hi:[1,0]
	v_rcp_f32_e32 v156, v156
	v_rcp_f32_e32 v157, v157
	v_rcp_f32_e32 v158, v158
	v_rcp_f32_e32 v159, v159
	v_rcp_f32_e32 v160, v160
	v_rcp_f32_e32 v161, v161
	v_rcp_f32_e32 v162, v162
	v_rcp_f32_e32 v163, v163
	v_pk_mul_f32 v[156:157], v[96:97], v[156:157]
	v_pk_mul_f32 v[158:159], v[98:99], v[158:159]
	v_pk_mul_f32 v[160:161], v[88:89], v[160:161]
	v_pk_mul_f32 v[162:163], v[90:91], v[162:163]
	v_pk_mul_f32 v[92:93], v[156:157], v[92:93]
	v_pk_mul_f32 v[94:95], v[158:159], v[94:95]
	v_pk_mul_f32 v[96:97], v[160:161], v[84:85]
	v_mul_f32_e32 v90, v162, v86
	v_mul_f32_e32 v87, v163, v87
	v_lshl_add_u64 v[88:89], v[100:101], 0, v[116:117]
	v_cvt_pk_bf16_f32 v84, v92, v93
	v_cvt_pk_bf16_f32 v85, v94, v95
	v_cvt_pk_bf16_f32 v86, v96, v97
	v_cvt_pk_bf16_f32 v87, v90, v87
	global_store_dwordx4 v[88:89], v[84:87], off
	s_nop 1
	v_add_u32_e32 v84, 48, v147
	v_mad_i64_i32 v[84:85], s[42:43], v84, s40, v[142:143]
	v_pk_mul_f32 v[156:157], v[80:81], v[164:165]
	v_pk_mul_f32 v[158:159], v[82:83], v[164:165]
	v_pk_mul_f32 v[160:161], v[72:73], v[164:165]
	v_pk_mul_f32 v[162:163], v[74:75], v[164:165]
	v_exp_f32_e32 v156, v156
	v_exp_f32_e32 v157, v157
	v_exp_f32_e32 v158, v158
	v_exp_f32_e32 v159, v159
	v_exp_f32_e32 v160, v160
	v_exp_f32_e32 v161, v161
	v_exp_f32_e32 v162, v162
	v_exp_f32_e32 v163, v163
	v_pk_add_f32 v[156:157], v[156:157], 1.0 op_sel_hi:[1,0]
	v_pk_add_f32 v[158:159], v[158:159], 1.0 op_sel_hi:[1,0]
	v_pk_add_f32 v[160:161], v[160:161], 1.0 op_sel_hi:[1,0]
	v_pk_add_f32 v[162:163], v[162:163], 1.0 op_sel_hi:[1,0]
	v_rcp_f32_e32 v156, v156
	v_rcp_f32_e32 v157, v157
	v_rcp_f32_e32 v158, v158
	v_rcp_f32_e32 v159, v159
	v_rcp_f32_e32 v160, v160
	v_rcp_f32_e32 v161, v161
	v_rcp_f32_e32 v162, v162
	v_rcp_f32_e32 v163, v163
	v_pk_mul_f32 v[156:157], v[80:81], v[156:157]
	v_pk_mul_f32 v[158:159], v[82:83], v[158:159]
	v_pk_mul_f32 v[160:161], v[72:73], v[160:161]
	v_pk_mul_f32 v[162:163], v[74:75], v[162:163]
	v_pk_mul_f32 v[76:77], v[156:157], v[76:77]
	v_pk_mul_f32 v[78:79], v[158:159], v[78:79]
	v_pk_mul_f32 v[80:81], v[160:161], v[68:69]
	v_mul_f32_e32 v74, v162, v70
	v_mul_f32_e32 v71, v163, v71
	v_lshl_add_u64 v[72:73], v[84:85], 0, v[116:117]
	v_cvt_pk_bf16_f32 v68, v76, v77
	v_cvt_pk_bf16_f32 v69, v78, v79
	v_cvt_pk_bf16_f32 v70, v80, v81
	v_cvt_pk_bf16_f32 v71, v74, v71
	global_store_dwordx4 v[72:73], v[68:71], off
	s_nop 1
	v_add_u32_e32 v68, 0x80, v147
	v_mad_i64_i32 v[68:69], s[42:43], v68, s40, v[142:143]
	v_pk_mul_f32 v[156:157], v[64:65], v[164:165]
	v_pk_mul_f32 v[158:159], v[66:67], v[164:165]
	v_pk_mul_f32 v[160:161], v[56:57], v[164:165]
	v_pk_mul_f32 v[162:163], v[58:59], v[164:165]
	v_exp_f32_e32 v156, v156
	v_exp_f32_e32 v157, v157
	v_exp_f32_e32 v158, v158
	v_exp_f32_e32 v159, v159
	v_exp_f32_e32 v160, v160
	v_exp_f32_e32 v161, v161
	v_exp_f32_e32 v162, v162
	v_exp_f32_e32 v163, v163
	v_pk_add_f32 v[156:157], v[156:157], 1.0 op_sel_hi:[1,0]
	v_pk_add_f32 v[158:159], v[158:159], 1.0 op_sel_hi:[1,0]
	v_pk_add_f32 v[160:161], v[160:161], 1.0 op_sel_hi:[1,0]
	v_pk_add_f32 v[162:163], v[162:163], 1.0 op_sel_hi:[1,0]
	v_rcp_f32_e32 v156, v156
	v_rcp_f32_e32 v157, v157
	v_rcp_f32_e32 v158, v158
	v_rcp_f32_e32 v159, v159
	v_rcp_f32_e32 v160, v160
	v_rcp_f32_e32 v161, v161
	v_rcp_f32_e32 v162, v162
	v_rcp_f32_e32 v163, v163
	v_pk_mul_f32 v[156:157], v[64:65], v[156:157]
; __device__ __forceinline__ unsigned cvt_pk_bf16(float lo, float hi) { unsigned r; asm volatile("v_cvt_pk_bf16_f32 %0, %1, %2" : "=v"(r) : "v"(lo), "v"(hi)); return r; }
; #define PG8_WAIT_V(n) asm volatile("s_waitcnt vmcnt(" #n ")" ::: "memory")
; #define PG8_BAR __builtin_amdgcn_s_barrier()
;     __device__ __forceinline__ void operator()(const f32x4 (&acc)[2][2][4][2], const Unit& u, int wr, int wc, int fr, int fq) const {
;     ...
;         for (int ai = 0; ai < 2; ++ai)
; #pragma unroll
;             for (int m = 0; m < 4; ++m) { bf16_t* rowp = T + (size_t)(row0 + ai * HALF + m * 16) * ldc + col0; float t[8];
; #pragma unroll
;                 for (int n = 0; n < 2; ++n) { const f32x4 a = acc[ai][0][m][n], b = acc[ai][1][m][n];
; #pragma unroll
;                     for (int e = 0; e < 4; ++e) t[4 * n + e] = a[e] * __builtin_amdgcn_rcpf(1.0f + __expf(-a[e])) * b[e]; }
;                 u32x4 w; w.x = cvt_pk_bf16(t[0], t[1]); w.y = cvt_pk_bf16(t[2], t[3]); w.z = cvt_pk_bf16(t[4], t[5]); w.w = cvt_pk_bf16(t[6], t[7]);
;                 *(u32x4*)rowp = w; }
; template <class Epi, class Sched, bool ALIGN_EPI = false, bool SP2 = false>
; __device__ __forceinline__ void gemm_phase(PG8_LAS unsigned char* lds, const Gemm g, const Sched& S, const Epi& E) {
;     ...
;         if constexpr (ALIGN_EPI) { if (wr == 0) PG8_BAR; }
;         if constexpr (!Epi::AFTER_DRAIN) { E(acc, cur, wr, wc, fr, fq); S.done(cur); }
;         if (!has_next) break;
; #pragma unroll
;         for (int a = 0; a < 2; ++a)
; #pragma unroll
;             for (int b = 0; b < 2; ++b)
; #pragma unroll
;                 for (int m = 0; m < 4; ++m)
; #pragma unroll
;                     for (int n = 0; n < 2; ++n) acc[a][b][m][n] = (f32x4){0.f, 0.f, 0.f, 0.f};
;         cur = nxt; cA = nA; cB = nB; ++ui;
;         if constexpr (ALIGN_EPI) { if (wr == 1) PG8_BAR; }
;     }
;     PG8_WAIT_V(0);
;     if constexpr (!ALIGN_EPI) { if (wr == 0) PG8_BAR; }
;     PG8_BAR;
	v_pk_mul_f32 v[158:159], v[66:67], v[158:159]
	v_pk_mul_f32 v[160:161], v[56:57], v[160:161]
	v_pk_mul_f32 v[162:163], v[58:59], v[162:163]
	v_pk_mul_f32 v[60:61], v[156:157], v[60:61]
	v_pk_mul_f32 v[62:63], v[158:159], v[62:63]
	v_pk_mul_f32 v[64:65], v[160:161], v[52:53]
	v_mul_f32_e32 v58, v162, v54
	v_mul_f32_e32 v55, v163, v55
	v_lshl_add_u64 v[56:57], v[68:69], 0, v[116:117]
	v_cvt_pk_bf16_f32 v52, v60, v61
	v_cvt_pk_bf16_f32 v53, v62, v63
	v_cvt_pk_bf16_f32 v54, v64, v65
	v_cvt_pk_bf16_f32 v55, v58, v55
	global_store_dwordx4 v[56:57], v[52:55], off
	s_nop 1
	v_add_u32_e32 v52, 0x90, v147
	v_mad_i64_i32 v[52:53], s[42:43], v52, s40, v[142:143]
	v_pk_mul_f32 v[156:157], v[48:49], v[164:165]
	v_pk_mul_f32 v[158:159], v[50:51], v[164:165]
	v_pk_mul_f32 v[160:161], v[40:41], v[164:165]
	v_pk_mul_f32 v[162:163], v[42:43], v[164:165]
	v_exp_f32_e32 v156, v156
	v_exp_f32_e32 v157, v157
	v_exp_f32_e32 v158, v158
	v_exp_f32_e32 v159, v159
	v_exp_f32_e32 v160, v160
	v_exp_f32_e32 v161, v161
	v_exp_f32_e32 v162, v162
	v_exp_f32_e32 v163, v163
	v_pk_add_f32 v[156:157], v[156:157], 1.0 op_sel_hi:[1,0]
	v_pk_add_f32 v[158:159], v[158:159], 1.0 op_sel_hi:[1,0]
	v_pk_add_f32 v[160:161], v[160:161], 1.0 op_sel_hi:[1,0]
	v_pk_add_f32 v[162:163], v[162:163], 1.0 op_sel_hi:[1,0]
	v_rcp_f32_e32 v156, v156
	v_rcp_f32_e32 v157, v157
	v_rcp_f32_e32 v158, v158
	v_rcp_f32_e32 v159, v159
	v_rcp_f32_e32 v160, v160
	v_rcp_f32_e32 v161, v161
	v_rcp_f32_e32 v162, v162
	v_rcp_f32_e32 v163, v163
	v_pk_mul_f32 v[156:157], v[48:49], v[156:157]
	v_pk_mul_f32 v[158:159], v[50:51], v[158:159]
	v_pk_mul_f32 v[160:161], v[40:41], v[160:161]
	v_pk_mul_f32 v[162:163], v[42:43], v[162:163]
	v_pk_mul_f32 v[44:45], v[156:157], v[44:45]
	v_pk_mul_f32 v[46:47], v[158:159], v[46:47]
	v_pk_mul_f32 v[48:49], v[160:161], v[36:37]
	v_mul_f32_e32 v42, v162, v38
	v_mul_f32_e32 v39, v163, v39
	v_lshl_add_u64 v[40:41], v[52:53], 0, v[116:117]
	v_cvt_pk_bf16_f32 v36, v44, v45
	v_cvt_pk_bf16_f32 v37, v46, v47
	v_cvt_pk_bf16_f32 v38, v48, v49
	v_cvt_pk_bf16_f32 v39, v42, v39
	global_store_dwordx4 v[40:41], v[36:39], off
	s_nop 1
	v_add_u32_e32 v36, 0xa0, v147
	v_mad_i64_i32 v[36:37], s[42:43], v36, s40, v[142:143]
	v_pk_mul_f32 v[156:157], v[32:33], v[164:165]
	v_pk_mul_f32 v[158:159], v[34:35], v[164:165]
	v_pk_mul_f32 v[160:161], v[24:25], v[164:165]
	v_pk_mul_f32 v[162:163], v[26:27], v[164:165]
	v_exp_f32_e32 v156, v156
	v_exp_f32_e32 v157, v157
	v_exp_f32_e32 v158, v158
	v_exp_f32_e32 v159, v159
	v_exp_f32_e32 v160, v160
	v_exp_f32_e32 v161, v161
	v_exp_f32_e32 v162, v162
	v_exp_f32_e32 v163, v163
	v_pk_add_f32 v[156:157], v[156:157], 1.0 op_sel_hi:[1,0]
	v_pk_add_f32 v[158:159], v[158:159], 1.0 op_sel_hi:[1,0]
	v_pk_add_f32 v[160:161], v[160:161], 1.0 op_sel_hi:[1,0]
	v_pk_add_f32 v[162:163], v[162:163], 1.0 op_sel_hi:[1,0]
	v_rcp_f32_e32 v156, v156
	v_rcp_f32_e32 v157, v157
	v_rcp_f32_e32 v158, v158
	v_rcp_f32_e32 v159, v159
	v_rcp_f32_e32 v160, v160
	v_rcp_f32_e32 v161, v161
	v_rcp_f32_e32 v162, v162
	v_rcp_f32_e32 v163, v163
	v_pk_mul_f32 v[156:157], v[32:33], v[156:157]
	v_pk_mul_f32 v[158:159], v[34:35], v[158:159]
	v_pk_mul_f32 v[160:161], v[24:25], v[160:161]
	v_pk_mul_f32 v[162:163], v[26:27], v[162:163]
	v_pk_mul_f32 v[28:29], v[156:157], v[28:29]
	v_pk_mul_f32 v[30:31], v[158:159], v[30:31]
	v_pk_mul_f32 v[32:33], v[160:161], v[20:21]
	v_mul_f32_e32 v26, v162, v22
	v_mul_f32_e32 v23, v163, v23
	v_lshl_add_u64 v[24:25], v[36:37], 0, v[116:117]
	v_cvt_pk_bf16_f32 v20, v28, v29
	v_cvt_pk_bf16_f32 v21, v30, v31
	v_cvt_pk_bf16_f32 v22, v32, v33
	v_cvt_pk_bf16_f32 v23, v26, v23
	global_store_dwordx4 v[24:25], v[20:23], off
	s_nop 1
	v_add_u32_e32 v20, 0xb0, v147
	v_mad_i64_i32 v[20:21], s[42:43], v20, s40, v[142:143]
	s_mov_b64 s[42:43], -1
	v_pk_mul_f32 v[156:157], v[16:17], v[164:165]
	v_pk_mul_f32 v[158:159], v[18:19], v[164:165]
	v_pk_mul_f32 v[160:161], v[8:9], v[164:165]
	v_pk_mul_f32 v[162:163], v[10:11], v[164:165]
	v_exp_f32_e32 v156, v156
	v_exp_f32_e32 v157, v157
	v_exp_f32_e32 v158, v158
	v_exp_f32_e32 v159, v159
	v_exp_f32_e32 v160, v160
	v_exp_f32_e32 v161, v161
	v_exp_f32_e32 v162, v162
	v_exp_f32_e32 v163, v163
	v_pk_add_f32 v[156:157], v[156:157], 1.0 op_sel_hi:[1,0]
	v_pk_add_f32 v[158:159], v[158:159], 1.0 op_sel_hi:[1,0]
	v_pk_add_f32 v[160:161], v[160:161], 1.0 op_sel_hi:[1,0]
	v_pk_add_f32 v[162:163], v[162:163], 1.0 op_sel_hi:[1,0]
	v_rcp_f32_e32 v156, v156
	v_rcp_f32_e32 v157, v157
	v_rcp_f32_e32 v158, v158
	v_rcp_f32_e32 v159, v159
	v_rcp_f32_e32 v160, v160
	v_rcp_f32_e32 v161, v161
	v_rcp_f32_e32 v162, v162
	v_rcp_f32_e32 v163, v163
	v_pk_mul_f32 v[156:157], v[16:17], v[156:157]
	v_pk_mul_f32 v[158:159], v[18:19], v[158:159]
	v_pk_mul_f32 v[160:161], v[8:9], v[160:161]
	v_pk_mul_f32 v[162:163], v[10:11], v[162:163]
	v_pk_mul_f32 v[12:13], v[156:157], v[12:13]
	v_pk_mul_f32 v[14:15], v[158:159], v[14:15]
	v_pk_mul_f32 v[16:17], v[160:161], v[4:5]
	v_mul_f32_e32 v10, v162, v6
	v_mul_f32_e32 v7, v163, v7
	v_lshl_add_u64 v[8:9], v[20:21], 0, v[116:117]
	v_cvt_pk_bf16_f32 v4, v12, v13
	v_cvt_pk_bf16_f32 v5, v14, v15
	v_cvt_pk_bf16_f32 v6, v16, v17
	v_cvt_pk_bf16_f32 v7, v10, v7
	global_store_dwordx4 v[8:9], v[4:7], off
	s_cbranch_vccnz .LBB0_333
	s_andn2_b64 vcc, exec, s[6:7]
	s_cbranch_vccnz .LBB0_332
	s_nop 0
	s_branch .LBB0_332
.LBB0_343:
	s_waitcnt vmcnt(0)
	v_readlane_b32 s88, v255, 13
	v_readlane_b32 s90, v255, 15
	v_readlane_b32 s83, v255, 12
	v_readlane_b32 s89, v255, 14
	v_readlane_b32 s91, v255, 16
	v_readlane_b32 s45, v255, 2
	s_mov_b32 s58, 0xf800000
	s_mov_b32 s59, 0x615c000
	s_and_b64 vcc, exec, s[34:35]
	s_cbranch_vccz .Lg5_nb
	s_barrier
.Lg5_nb:
	s_barrier
